# stack: + batched sample epilogues in tail units (p4/p12), sample rows of norm 5/13 in barrier shadow, phase-10 sample-row scale/shift loads batched
# speedup vs baseline: 1.0072x; 1.0072x over previous
.LBB0_1151:
	v_lshl_add_u64 v[32:33], v[22:23], 0, v[48:49]
	v_add_co_u32_e64 v60, s[0:1], s3, v32
	v_lshl_add_u64 v[34:35], v[20:21], 0, v[48:49]
	s_nop 0
	v_addc_co_u32_e64 v61, s[0:1], 0, v33, s[0:1]
	v_add_co_u32_e64 v76, s[0:1], s6, v32
	v_add_co_u32_e32 v34, vcc, 0x4000000, v34
	s_nop 0
	v_addc_co_u32_e64 v77, s[0:1], 0, v33, s[0:1]
	v_add_co_u32_e64 v92, s[0:1], s7, v32
	v_ashrrev_i32_e32 v44, 2, v50
	s_nop 0
	v_addc_co_u32_e64 v93, s[0:1], 0, v33, s[0:1]
	v_add_co_u32_e64 v108, s[0:1], s9, v32
	v_add_u32_e32 v162, 0x4000, v50
	s_nop 0
	v_addc_co_u32_e64 v109, s[0:1], 0, v33, s[0:1]
	v_add_co_u32_e64 v124, s[0:1], s28, v32
	v_addc_co_u32_e32 v35, vcc, 0, v35, vcc
	s_nop 0
	v_addc_co_u32_e64 v125, s[0:1], 0, v33, s[0:1]
	v_add_co_u32_e64 v140, s[0:1], s29, v32
	v_add_u32_e32 v51, 8, v44
	s_nop 0
	v_addc_co_u32_e64 v141, s[0:1], 0, v33, s[0:1]
	v_add_co_u32_e64 v158, s[0:1], s30, v32
	v_ashrrev_i32_e32 v163, 31, v162
	v_add_co_u32_e32 v192, vcc, 0xe600000, v32
	v_addc_co_u32_e64 v159, s[0:1], 0, v33, s[0:1]
	v_mad_i64_i32 v[180:181], s[0:1], v51, s31, v[24:25]
	v_lshlrev_b64 v[182:183], 11, v[162:163]
	v_addc_co_u32_e32 v193, vcc, 0, v33, vcc
	global_load_dwordx4 v[44:47], v[60:61], off
	global_load_dwordx4 v[52:55], v[60:61], off offset:1024
	global_load_dwordx4 v[56:59], v[60:61], off offset:2048
	s_nop 0
	global_load_dwordx4 v[60:63], v[60:61], off offset:3072
	s_nop 0
	global_load_dwordx4 v[64:67], v[76:77], off
	global_load_dwordx4 v[68:71], v[76:77], off offset:1024
	global_load_dwordx4 v[72:75], v[76:77], off offset:2048
	s_nop 0
	global_load_dwordx4 v[76:79], v[76:77], off offset:3072
	s_nop 0
	global_load_dwordx4 v[80:83], v[92:93], off
	global_load_dwordx4 v[84:87], v[92:93], off offset:1024
	global_load_dwordx4 v[88:91], v[92:93], off offset:2048
	s_nop 0
	global_load_dwordx4 v[92:95], v[92:93], off offset:3072
	s_nop 0
	global_load_dwordx4 v[96:99], v[108:109], off
	global_load_dwordx4 v[100:103], v[108:109], off offset:1024
	global_load_dwordx4 v[104:107], v[108:109], off offset:2048
	s_nop 0
	global_load_dwordx4 v[108:111], v[108:109], off offset:3072
	s_nop 0
	global_load_dwordx4 v[112:115], v[124:125], off
	global_load_dwordx4 v[116:119], v[124:125], off offset:1024
	global_load_dwordx4 v[120:123], v[124:125], off offset:2048
	s_nop 0
	global_load_dwordx4 v[124:127], v[124:125], off offset:3072
	s_nop 0
	global_load_dwordx4 v[128:131], v[140:141], off
	global_load_dwordx4 v[132:135], v[140:141], off offset:1024
	global_load_dwordx4 v[136:139], v[140:141], off offset:2048
	s_nop 0
	global_load_dwordx4 v[140:143], v[140:141], off offset:3072
	s_nop 0
	global_load_dwordx4 v[146:149], v[158:159], off
	global_load_dwordx4 v[150:153], v[158:159], off offset:1024
	global_load_dwordx4 v[154:157], v[158:159], off offset:2048
	s_nop 0
	global_load_dwordx4 v[158:161], v[158:159], off offset:3072
	s_nop 0
	global_load_dwordx4 v[162:165], v[34:35], off
	global_load_dwordx4 v[166:169], v[34:35], off offset:1024
	global_load_dwordx4 v[170:173], v[34:35], off offset:2048
	global_load_dwordx4 v[176:179], v[34:35], off offset:3072
	v_lshl_add_u64 v[196:197], v[180:181], 0, s[16:17]
	v_lshl_add_u64 v[198:199], v[180:181], 0, s[20:21]
	v_lshl_add_u64 v[32:33], v[18:19], 0, v[182:183]
	global_load_dwordx4 v[180:183], v[192:193], off
	global_load_dwordx4 v[184:187], v[192:193], off offset:1024
	global_load_dwordx4 v[188:191], v[192:193], off offset:2048
	s_nop 0
	global_load_dwordx4 v[192:195], v[192:193], off offset:3072
	v_lshl_add_u64 v[200:201], v[196:197], 0, v[16:17]
	v_lshl_add_u64 v[202:203], v[198:199], 0, v[16:17]
	v_lshl_add_u64 v[204:205], v[196:197], 0, v[26:27]
	v_lshl_add_u64 v[206:207], v[198:199], 0, v[26:27]
	v_add_u32_e32 v50, s8, v50
	v_lshl_add_u64 v[20:21], v[20:21], 0, s[12:13]
	v_lshl_add_u64 v[22:23], v[22:23], 0, s[12:13]
	s_waitcnt vmcnt(3)
	v_pk_add_f32 v[164:165], v[164:165], v[182:183]
	v_pk_add_f32 v[162:163], v[162:163], v[180:181]
	s_waitcnt vmcnt(2)
	v_pk_add_f32 v[168:169], v[168:169], v[186:187]
	v_pk_add_f32 v[166:167], v[166:167], v[184:185]
	s_waitcnt vmcnt(1)
	v_pk_add_f32 v[172:173], v[172:173], v[190:191]
	v_pk_add_f32 v[170:171], v[170:171], v[188:189]
	s_waitcnt vmcnt(0)
	v_pk_add_f32 v[178:179], v[178:179], v[194:195]
	v_pk_add_f32 v[176:177], v[176:177], v[192:193]
	v_pk_add_f32 v[46:47], v[164:165], v[46:47]
	v_pk_add_f32 v[44:45], v[162:163], v[44:45]
	v_pk_add_f32 v[54:55], v[168:169], v[54:55]
	v_pk_add_f32 v[52:53], v[166:167], v[52:53]
	v_pk_add_f32 v[58:59], v[172:173], v[58:59]
	v_pk_add_f32 v[56:57], v[170:171], v[56:57]
	v_pk_add_f32 v[62:63], v[178:179], v[62:63]
	v_pk_add_f32 v[60:61], v[176:177], v[60:61]
	v_pk_add_f32 v[46:47], v[46:47], v[66:67]
	v_pk_add_f32 v[44:45], v[44:45], v[64:65]
	v_pk_add_f32 v[54:55], v[54:55], v[70:71]
	v_pk_add_f32 v[52:53], v[52:53], v[68:69]
	v_pk_add_f32 v[58:59], v[58:59], v[74:75]
	v_pk_add_f32 v[56:57], v[56:57], v[72:73]
	v_pk_add_f32 v[62:63], v[62:63], v[78:79]
	v_pk_add_f32 v[60:61], v[60:61], v[76:77]
	v_pk_add_f32 v[46:47], v[46:47], v[82:83]
	v_pk_add_f32 v[44:45], v[44:45], v[80:81]
	v_pk_add_f32 v[54:55], v[54:55], v[86:87]
	v_pk_add_f32 v[52:53], v[52:53], v[84:85]
	v_pk_add_f32 v[58:59], v[58:59], v[90:91]
	v_pk_add_f32 v[56:57], v[56:57], v[88:89]
	v_pk_add_f32 v[62:63], v[62:63], v[94:95]
	v_pk_add_f32 v[60:61], v[60:61], v[92:93]
	v_pk_add_f32 v[46:47], v[46:47], v[98:99]
	v_pk_add_f32 v[44:45], v[44:45], v[96:97]
	v_pk_add_f32 v[54:55], v[54:55], v[102:103]
	v_pk_add_f32 v[52:53], v[52:53], v[100:101]
	v_pk_add_f32 v[58:59], v[58:59], v[106:107]
	v_pk_add_f32 v[56:57], v[56:57], v[104:105]
	v_pk_add_f32 v[62:63], v[62:63], v[110:111]
	v_pk_add_f32 v[60:61], v[60:61], v[108:109]
	v_pk_add_f32 v[46:47], v[46:47], v[114:115]
	v_pk_add_f32 v[44:45], v[44:45], v[112:113]
	v_pk_add_f32 v[54:55], v[54:55], v[118:119]
	v_pk_add_f32 v[52:53], v[52:53], v[116:117]
	v_pk_add_f32 v[58:59], v[58:59], v[122:123]
	v_pk_add_f32 v[56:57], v[56:57], v[120:121]
	v_pk_add_f32 v[62:63], v[62:63], v[126:127]
	v_pk_add_f32 v[60:61], v[60:61], v[124:125]
	v_pk_add_f32 v[46:47], v[46:47], v[130:131]
	v_pk_add_f32 v[44:45], v[44:45], v[128:129]
	v_pk_add_f32 v[54:55], v[54:55], v[134:135]
	v_pk_add_f32 v[52:53], v[52:53], v[132:133]
	v_pk_add_f32 v[58:59], v[58:59], v[138:139]
	v_pk_add_f32 v[56:57], v[56:57], v[136:137]
	v_pk_add_f32 v[62:63], v[62:63], v[142:143]
	v_pk_add_f32 v[60:61], v[60:61], v[140:141]
	v_pk_add_f32 v[46:47], v[46:47], v[148:149]
	v_pk_add_f32 v[44:45], v[44:45], v[146:147]
	v_pk_add_f32 v[54:55], v[54:55], v[152:153]
	v_pk_add_f32 v[52:53], v[52:53], v[150:151]
	v_pk_add_f32 v[58:59], v[58:59], v[156:157]
	v_pk_add_f32 v[56:57], v[56:57], v[154:155]
	v_pk_add_f32 v[62:63], v[62:63], v[160:161]
	v_pk_add_f32 v[60:61], v[60:61], v[158:159]
	global_store_dwordx4 v[34:35], v[44:47], off
	global_store_dwordx4 v[34:35], v[52:55], off offset:1024
	global_store_dwordx4 v[34:35], v[56:59], off offset:2048
	global_store_dwordx4 v[34:35], v[60:63], off offset:3072
	v_pk_mul_f32 v[34:35], v[46:47], v[46:47]
	v_pk_mul_f32 v[72:73], v[44:45], v[44:45]
	v_pk_mul_f32 v[64:65], v[54:55], v[54:55]
	v_pk_mul_f32 v[74:75], v[52:53], v[52:53]
	v_mul_f32_e32 v66, v57, v57
	v_mul_f32_e32 v68, v59, v59
	v_pk_mov_b32 v[76:77], v[72:73], v[34:35] op_sel:[1,0]
	v_mov_b32_e32 v73, v35
	v_pk_mov_b32 v[34:35], v[74:75], v[64:65] op_sel:[1,0]
	v_mov_b32_e32 v75, v65
	v_pk_fma_f32 v[78:79], v[56:57], v[56:57], v[66:67] op_sel_hi:[1,1,0]
	v_pk_fma_f32 v[80:81], v[58:59], v[58:59], v[68:69] op_sel_hi:[1,1,0]
	global_load_dwordx4 v[64:67], v[200:201], off
	global_load_dwordx4 v[68:71], v[202:203], off
	global_load_dwordx4 v[100:103], v[204:205], off
	global_load_dwordx4 v[104:107], v[206:207], off
	v_lshl_add_u64 v[128:129], v[196:197], 0, v[28:29]
	v_lshl_add_u64 v[130:131], v[198:199], 0, v[28:29]
	global_load_dwordx4 v[108:111], v[128:129], off
	global_load_dwordx4 v[112:115], v[130:131], off
	v_lshl_add_u64 v[132:133], v[196:197], 0, v[30:31]
	v_lshl_add_u64 v[134:135], v[198:199], 0, v[30:31]
	global_load_dwordx4 v[116:119], v[132:133], off
	global_load_dwordx4 v[120:123], v[134:135], off
	v_pk_add_f32 v[72:73], v[76:77], v[72:73]
	v_pk_add_f32 v[34:35], v[34:35], v[74:75]
	v_mul_f32_e32 v51, v60, v60
	v_mul_f32_e32 v82, v61, v61
	v_mul_f32_e32 v83, v62, v62
	v_mul_f32_e32 v84, v63, v63
	v_pk_add_f32 v[72:73], v[72:73], v[72:73] op_sel:[0,1] op_sel_hi:[1,0]
	v_pk_add_f32 v[34:35], v[34:35], v[34:35] op_sel:[0,1] op_sel_hi:[1,0]
	v_mov_b32_e32 v79, v83
	v_mov_b32_e32 v81, v84
	v_mov_b32_e32 v73, v51
	v_mov_b32_e32 v35, v82
	v_pk_add_f32 v[74:75], v[78:79], v[80:81]
	v_pk_add_f32 v[34:35], v[72:73], v[34:35]
	s_waitcnt vmcnt(0)
	v_pk_add_f32 v[64:65], v[64:65], 1.0 op_sel_hi:[1,0]
	v_pk_add_f32 v[34:35], v[34:35], v[74:75]
	v_pk_add_f32 v[66:67], v[66:67], 1.0 op_sel_hi:[1,0]
	v_add_f32_e32 v34, v34, v35
	s_nop 1
	v_add_f32_dpp v34, v34, v34 quad_perm:[1,0,3,2] row_mask:0xf bank_mask:0xf
	s_nop 1
	v_add_f32_dpp v34, v34, v34 quad_perm:[2,3,0,1] row_mask:0xf bank_mask:0xf
	s_nop 1
	v_add_f32_dpp v34, v34, v34 row_half_mirror row_mask:0xf bank_mask:0xf
	s_nop 1
	v_add_f32_dpp v34, v34, v34 row_ror:8 row_mask:0xf bank_mask:0xf
	v_mov_b32_e32 v35, v34
	s_nop 1
	v_permlane16_swap_b32_e32 v35, v34
	v_add_f32_e32 v34, v34, v35
	v_mov_b32_e32 v35, v34
	s_nop 1
	v_permlane32_swap_b32_e32 v35, v34
	v_add_f32_e32 v34, v34, v35
	v_fmamk_f32 v34, v34, 0x3a800000, v42
	v_mul_f32_e32 v35, 0x4f800000, v34
	v_cmp_gt_f32_e32 vcc, s36, v34
	s_nop 1
	v_cndmask_b32_e32 v34, v34, v35, vcc
	v_sqrt_f32_e32 v35, v34
	s_nop 0
	v_add_u32_e32 v51, -1, v35
	v_add_u32_e32 v72, 1, v35
	v_fma_f32 v73, -v51, v35, v34
	v_fma_f32 v74, -v72, v35, v34
	v_cmp_ge_f32_e64 s[0:1], 0, v73
	s_nop 1
	v_cndmask_b32_e64 v35, v35, v51, s[0:1]
	v_cmp_lt_f32_e64 s[0:1], 0, v74
	s_nop 1
	v_cndmask_b32_e64 v35, v35, v72, s[0:1]
	v_mul_f32_e32 v51, 0x37800000, v35
	v_cndmask_b32_e32 v35, v35, v51, vcc
	v_cmp_class_f32_e32 vcc, v34, v43
	s_nop 1
	v_cndmask_b32_e32 v34, v35, v34, vcc
	v_div_scale_f32 v35, s[0:1], v34, v34, 1.0
	v_rcp_f32_e32 v72, v35
	v_div_scale_f32 v51, vcc, 1.0, v34, 1.0
	v_fma_f32 v73, -v35, v72, 1.0
	v_fmac_f32_e32 v72, v73, v72
	v_mul_f32_e32 v73, v51, v72
	v_fma_f32 v74, -v35, v73, v51
	v_fmac_f32_e32 v73, v74, v72
	v_fma_f32 v35, -v35, v73, v51
	v_div_fmas_f32 v35, v35, v72, v73
	v_div_fixup_f32 v34, v35, v34, 1.0
	v_pk_mul_f32 v[44:45], v[44:45], v[34:35] op_sel_hi:[1,0]
	v_pk_mul_f32 v[46:47], v[46:47], v[34:35] op_sel_hi:[1,0]
	v_pk_mul_f32 v[44:45], v[0:1], v[44:45]
	v_pk_mul_f32 v[46:47], v[2:3], v[46:47]
	s_waitcnt vmcnt(0)
	v_pk_fma_f32 v[44:45], v[64:65], v[44:45], v[68:69]
	v_pk_fma_f32 v[46:47], v[66:67], v[46:47], v[70:71]
	v_cvt_pk_bf16_f32 v44, v44, v45
	v_pk_mul_f32 v[52:53], v[52:53], v[34:35] op_sel_hi:[1,0]
	v_cvt_pk_bf16_f32 v45, v46, v47
	global_store_dwordx2 v[32:33], v[44:45], off
	s_nop 1
	s_nop 0
	v_pk_mul_f32 v[54:55], v[54:55], v[34:35] op_sel_hi:[1,0]
	v_pk_mul_f32 v[52:53], v[4:5], v[52:53]
	v_pk_mul_f32 v[54:55], v[6:7], v[54:55]
	v_lshl_add_u64 v[68:69], v[196:197], 0, v[28:29]
	v_lshl_add_u64 v[70:71], v[198:199], 0, v[28:29]
	v_pk_mul_f32 v[56:57], v[56:57], v[34:35] op_sel_hi:[1,0]
	v_pk_mul_f32 v[58:59], v[58:59], v[34:35] op_sel_hi:[1,0]
	v_pk_mul_f32 v[56:57], v[8:9], v[56:57]
	v_pk_mul_f32 v[58:59], v[10:11], v[58:59]
	v_cmp_lt_i32_e32 vcc, s37, v50
	s_or_b64 s[14:15], vcc, s[14:15]
	v_pk_add_f32 v[44:45], v[100:101], 1.0 op_sel_hi:[1,0]
	v_pk_add_f32 v[46:47], v[102:103], 1.0 op_sel_hi:[1,0]
	v_pk_fma_f32 v[44:45], v[44:45], v[52:53], v[104:105]
	v_pk_fma_f32 v[46:47], v[46:47], v[54:55], v[106:107]
	v_cvt_pk_bf16_f32 v44, v44, v45
	v_lshl_add_u64 v[64:65], v[196:197], 0, v[30:31]
	v_cvt_pk_bf16_f32 v45, v46, v47
	global_store_dwordx2 v[32:33], v[44:45], off offset:512
	s_nop 1
	s_nop 0
	v_lshl_add_u64 v[66:67], v[198:199], 0, v[30:31]
	v_pk_add_f32 v[44:45], v[108:109], 1.0 op_sel_hi:[1,0]
	v_pk_add_f32 v[46:47], v[110:111], 1.0 op_sel_hi:[1,0]
	v_pk_fma_f32 v[44:45], v[56:57], v[44:45], v[112:113]
	v_pk_fma_f32 v[46:47], v[58:59], v[46:47], v[114:115]
	v_cvt_pk_bf16_f32 v44, v44, v45
	v_pk_mul_f32 v[56:57], v[62:63], v[34:35] op_sel_hi:[1,0]
	v_cvt_pk_bf16_f32 v45, v46, v47
	global_store_dwordx2 v[32:33], v[44:45], off offset:1024
	s_nop 1
	s_nop 0
	v_pk_mul_f32 v[34:35], v[60:61], v[34:35] op_sel_hi:[1,0]
	v_pk_mul_f32 v[56:57], v[14:15], v[56:57]
	v_pk_mul_f32 v[34:35], v[12:13], v[34:35]
	v_pk_add_f32 v[44:45], v[116:117], 1.0 op_sel_hi:[1,0]
	v_pk_add_f32 v[46:47], v[118:119], 1.0 op_sel_hi:[1,0]
	v_pk_fma_f32 v[34:35], v[34:35], v[44:45], v[120:121]
	v_pk_fma_f32 v[46:47], v[56:57], v[46:47], v[122:123]
	v_cvt_pk_bf16_f32 v34, v34, v35
	s_nop 0
	v_cvt_pk_bf16_f32 v35, v46, v47
	global_store_dwordx2 v[32:33], v[34:35], off offset:1536
	s_andn2_b64 exec, exec, s[14:15]
	s_cbranch_execnz .LBB0_1151
